# speedup vs baseline: 1.0079x; 1.0079x over previous
; __device__ __forceinline__ void finishSM(f32x16& p0, f32x16& p1, float alpha, float& l_reg, bf16x8& pa0, bf16x8& pa1, bf16x8& pa2, bf16x8& pa3) {
; #pragma unroll
;   for (int r = 0; r < 16; ++r) p1[r] = __builtin_amdgcn_exp2f(p1[r]);
;   float ps = 0;
; #pragma unroll
;   for (int r = 0; r < 16; ++r) ps += p0[r];
; #pragma unroll
;   for (int r = 0; r < 16; ++r) ps += p1[r];
;   { auto rr = __builtin_amdgcn_permlane32_swap(__float_as_uint(ps), __float_as_uint(ps), false, false);
;     ps = __uint_as_float(rr[0]) + __uint_as_float(rr[1]); }
;   l_reg = l_reg * alpha + ps;
;     ...
;   PK4(p0, 0, pa0); PK4(p0, 8, pa1); PK4(p1, 0, pa2); PK4(p1, 8, pa3);
;     ...
; }
; #pragma unroll
;   for (int r = 0; r < 16; ++r) { p0[r] = init; p1[r] = init; }
; #pragma unroll
;   for (int d0 = 0; d0 < 8; ++d0) { int cb = (d0 * 16 + hi * 8) * 2;
;     bf16x8 b0 = *reinterpret_cast<const bf16x8*>((const char*)Ks + KSWZ(r32, cb));
;     bf16x8 b1 = *reinterpret_cast<const bf16x8*>((const char*)Ks + KSWZ(32 + r32, cb));
;     p0 = __builtin_amdgcn_mfma_f32_32x32x16_bf16(b0, qr[d0], p0, 0, 0, 0);
;     p1 = __builtin_amdgcn_mfma_f32_32x32x16_bf16(b1, qr[d0], p1, 0, 0, 0); }
; }
; __device__ __forceinline__ void qkt_c(f32x16& p0, f32x16& p1, const bf16* Ks, const bf16x8* qr, int r32, int hi) {
;   const f32x16 cinit = {};
; #pragma unroll
;   for (int d0 = 0; d0 < 8; ++d0) { int cb = (d0 * 16 + hi * 8) * 2;
;     bf16x8 b0 = *reinterpret_cast<const bf16x8*>((const char*)Ks + KSWZ(r32, cb));
;     bf16x8 b1 = *reinterpret_cast<const bf16x8*>((const char*)Ks + KSWZ(32 + r32, cb));
;     p0 = __builtin_amdgcn_mfma_f32_32x32x16_bf16(b0, qr[d0], d0 == 0 ? cinit : p0, 0, 0, 0);
;     p1 = __builtin_amdgcn_mfma_f32_32x32x16_bf16(b1, qr[d0], d0 == 0 ? cinit : p1, 0, 0, 0); }
; }
.LBB0_118:
	s_add_i32 s2, s2, 2
	v_exp_f32_e32 v10, v88
	v_exp_f32_e32 v11, v89
	v_exp_f32_e32 v12, v90
	ds_read_b128 v[188:191], v201 offset:49152
	ds_read_b128 v[192:195], v201 offset:57344
	s_waitcnt lgkmcnt(3)
	v_mfma_f32_32x32x16_bf16 v[112:127], v[2:5], v[156:159], 0
	v_exp_f32_e32 v13, v91
	v_exp_f32_e32 v176, v92
	v_exp_f32_e32 v177, v93
	v_exp_f32_e32 v178, v94
	v_exp_f32_e32 v95, v95
	v_cvt_pk_bf16_f32 v92, v10, v11
	v_cvt_pk_bf16_f32 v93, v12, v13
	s_waitcnt lgkmcnt(2)
	v_mfma_f32_32x32x16_bf16 v[96:111], v[6:9], v[156:159], 0
	ds_read_b128 v[2:5], v202 offset:49152
	ds_read_b128 v[6:9], v202 offset:57344
	v_cvt_pk_bf16_f32 v94, v176, v177
	s_nop 1
	v_permlane32_swap_b32_e32 v92, v94
	s_waitcnt lgkmcnt(3)
	v_mfma_f32_32x32x16_bf16 v[112:127], v[188:191], v[152:155], v[112:127]
	s_waitcnt lgkmcnt(2)
	v_mfma_f32_32x32x16_bf16 v[96:111], v[192:195], v[152:155], v[96:111]
	ds_read_b128 v[188:191], v203 offset:49152
	ds_read_b128 v[192:195], v203 offset:57344
	v_add_u32_e32 v254, vcc_lo, v184
	v_add_u32_e32 v255, vcc_lo, v185
	s_waitcnt vmcnt(0)
	ds_write_b128 v254, v[160:163]
	s_waitcnt lgkmcnt(4)
	v_mfma_f32_32x32x16_bf16 v[112:127], v[2:5], v[148:151], v[112:127]
	s_waitcnt lgkmcnt(3)
	v_mfma_f32_32x32x16_bf16 v[96:111], v[6:9], v[148:151], v[96:111]
	ds_read_b128 v[2:5], v206 offset:49152
	ds_read_b128 v[6:9], v206 offset:57344
	ds_write_b128 v255, v[164:167]
	s_waitcnt lgkmcnt(5)
	v_mfma_f32_32x32x16_bf16 v[112:127], v[188:191], v[144:147], v[112:127]
	s_waitcnt lgkmcnt(4)
	v_mfma_f32_32x32x16_bf16 v[96:111], v[192:195], v[144:147], v[96:111]
	ds_read_b128 v[188:191], v204 offset:49152
	ds_read_b128 v[192:195], v204 offset:57344
	ds_write_b128 v198, v[168:171] offset:32768
	s_waitcnt lgkmcnt(5)
	v_mfma_f32_32x32x16_bf16 v[112:127], v[2:5], v[140:143], v[112:127]
	s_waitcnt lgkmcnt(4)
	v_mfma_f32_32x32x16_bf16 v[96:111], v[6:9], v[140:143], v[96:111]
	ds_read_b128 v[2:5], v205 offset:49152
	ds_read_b128 v[6:9], v205 offset:57344
	ds_write_b128 v199, v[172:175] offset:32768
	s_waitcnt lgkmcnt(5)
	v_mfma_f32_32x32x16_bf16 v[112:127], v[188:191], v[136:139], v[112:127]
	s_waitcnt lgkmcnt(4)
	v_mfma_f32_32x32x16_bf16 v[96:111], v[192:195], v[136:139], v[96:111]
	ds_read_b128 v[188:191], v207 offset:49152
	ds_read_b128 v[192:195], v207 offset:57344
	s_waitcnt lgkmcnt(4)
	v_mfma_f32_32x32x16_bf16 v[112:127], v[2:5], v[132:135], v[112:127]
	s_waitcnt lgkmcnt(3)
	v_mfma_f32_32x32x16_bf16 v[96:111], v[6:9], v[132:135], v[96:111]
	s_waitcnt lgkmcnt(1)
	v_mfma_f32_32x32x16_bf16 v[112:127], v[188:191], v[128:131], v[112:127]
	v_exp_f32_e32 v2, v80
	v_add_f32_e32 v80, 0, v223
	v_add_f32_e32 v80, v225, v80
	v_add_f32_e32 v80, v221, v80
	v_add_f32_e32 v80, v224, v80
	v_add_f32_e32 v80, v220, v80
	v_add_f32_e32 v80, v222, v80
	v_add_f32_e32 v80, v218, v80
	v_add_f32_e32 v80, v219, v80
	v_add_f32_e32 v80, v215, v80
	v_add_f32_e32 v80, v217, v80
	v_add_f32_e32 v80, v214, v80
	v_add_f32_e32 v80, v216, v80
	v_add_f32_e32 v80, v210, v80
	v_exp_f32_e32 v3, v81
	v_add_f32_e32 v80, v213, v80
	v_exp_f32_e32 v4, v82
	v_add_f32_e32 v80, v211, v80
	v_exp_f32_e32 v5, v83
	v_add_f32_e32 v80, v212, v80
	s_waitcnt lgkmcnt(0)
	v_mfma_f32_32x32x16_bf16 v[96:111], v[192:195], v[128:131], v[96:111]
	v_exp_f32_e32 v6, v84
	v_add_f32_e32 v80, v2, v80
	v_exp_f32_e32 v7, v85
	v_add_f32_e32 v80, v3, v80
	v_exp_f32_e32 v8, v86
	v_add_f32_e32 v80, v4, v80
	v_exp_f32_e32 v9, v87
	v_add_f32_e32 v80, v5, v80
	v_add_f32_e32 v80, v6, v80
	v_add_f32_e32 v80, v7, v80
	v_add_f32_e32 v80, v8, v80
	v_add_f32_e32 v80, v9, v80
	v_add_f32_e32 v80, v10, v80
	v_add_f32_e32 v80, v11, v80
	v_add_f32_e32 v80, v12, v80
	v_add_f32_e32 v80, v13, v80
	v_add_f32_e32 v80, v176, v80
	v_add_f32_e32 v80, v177, v80
	v_add_f32_e32 v80, v178, v80
	v_add_f32_e32 v80, v95, v80
	v_mov_b32_e32 v81, v80
	s_nop 1
	v_permlane32_swap_b32_e32 v80, v81
	v_add_f32_e32 v80, v80, v81
	v_add_f32_e32 v226, v183, v80
	v_cvt_pk_bf16_f32 v80, v223, v225
	v_cvt_pk_bf16_f32 v81, v221, v224
	v_cvt_pk_bf16_f32 v82, v220, v222
	v_cvt_pk_bf16_f32 v83, v218, v219
	v_cvt_pk_bf16_f32 v84, v215, v217
	v_cvt_pk_bf16_f32 v85, v214, v216
	v_cvt_pk_bf16_f32 v86, v210, v213
	v_cvt_pk_bf16_f32 v87, v211, v212
	v_cvt_pk_bf16_f32 v88, v2, v3
	v_cvt_pk_bf16_f32 v89, v4, v5
	v_cvt_pk_bf16_f32 v90, v6, v7
	v_cvt_pk_bf16_f32 v91, v8, v9
	v_cvt_pk_bf16_f32 v95, v178, v95
	s_nop 0
	v_permlane32_swap_b32_e32 v80, v82
	v_permlane32_swap_b32_e32 v81, v83
	v_permlane32_swap_b32_e32 v84, v86
	v_permlane32_swap_b32_e32 v85, v87
	v_permlane32_swap_b32_e32 v88, v90
	v_permlane32_swap_b32_e32 v89, v91
	v_permlane32_swap_b32_e32 v93, v95
	s_add_i32 s100, s2, 2
	s_mul_i32 s100, s100, 0x60000
	v_add_u32_e32 v254, s100, v14
	v_add_u32_e32 v255, s100, v15
	global_load_dwordx4 v[2:5], v254, s[58:59]
	global_load_dwordx4 v[6:9], v255, s[58:59]
	global_load_dwordx4 v[10:13], v254, s[8:9]
	global_load_dwordx4 v[176:179], v255, s[8:9]
	v_add_u32_e32 v255, vcc_hi, v208
	ds_read_b64_tr_b16 v[210:211], v255 offset:0
	ds_read_b64_tr_b16 v[212:213], v255 offset:0x800
	ds_read_b64_tr_b16 v[214:215], v255 offset:0x1000
	ds_read_b64_tr_b16 v[216:217], v255 offset:0x1800
	ds_read_b64_tr_b16 v[218:219], v255 offset:0x2000
	ds_read_b64_tr_b16 v[220:221], v255 offset:0x2800
	ds_read_b64_tr_b16 v[222:223], v255 offset:0x3000
	ds_read_b64_tr_b16 v[224:225], v255 offset:0x3800
	s_waitcnt lgkmcnt(0)
; #define SBAR() __builtin_amdgcn_sched_barrier(0)
; #define SWAIT() asm volatile("s_waitcnt vmcnt(4)" ::: "memory")
; #define RESC(a) do { if (!FIXED && __any((a) < 1.f)) { if (hi == 0) al_l[r32] = (a); asm volatile("s_waitcnt lgkmcnt(0)" ::: "memory"); \
;     _Pragma("unroll") for (int d = 0; d < 4; ++d) _Pragma("unroll") for (int r = 0; r < 16; ++r) o[d][r] *= al_l[crow(r, hi)]; } } while (0)
; #define MASK(P0, P1, t) do { if (BANDED) band_mask(P0, P1, rel00 + (t) * KVBLK, mlo, mhi); } while (0)
; template <int D0> __device__ __forceinline__ void pv_one(f32x16& od, int vb, bf16x8 pa0, bf16x8 pa1, bf16x8 pa2, bf16x8 pa3) {
;   const s16x4 l0 = tr_read<v_rd_off(D0, 0, 0)>(vb), h0 = tr_read<v_rd_off(D0, 0, 1)>(vb), l1 = tr_read<v_rd_off(D0, 1, 0)>(vb), h1 = tr_read<v_rd_off(D0, 1, 1)>(vb);
;   const s16x4 l2 = tr_read<v_rd_off(D0, 2, 0)>(vb), h2 = tr_read<v_rd_off(D0, 2, 1)>(vb), l3 = tr_read<v_rd_off(D0, 3, 0)>(vb), h3 = tr_read<v_rd_off(D0, 3, 1)>(vb);
;   asm volatile("s_waitcnt lgkmcnt(0)" ::: "memory"); SBAR();
;     ...
;   od = __builtin_amdgcn_mfma_f32_32x32x16_bf16(pa0, PK(l0, h0), od, 0, 0, 0);
;   od = __builtin_amdgcn_mfma_f32_32x32x16_bf16(pa1, PK(l1, h1), od, 0, 0, 0);
;   od = __builtin_amdgcn_mfma_f32_32x32x16_bf16(pa2, PK(l2, h2), od, 0, 0, 0);
;   od = __builtin_amdgcn_mfma_f32_32x32x16_bf16(pa3, PK(l3, h3), od, 0, 0, 0);
;     ...
; }
; __device__ __forceinline__ void pv_d0(f32x16* o, int vb, bf16x8 pa0, bf16x8 pa1, bf16x8 pa2, bf16x8 pa3) {
;   pv_one<0>(o[0], vb, pa0, pa1, pa2, pa3); pv_one<1>(o[1], vb, pa0, pa1, pa2, pa3); pv_one<2>(o[2], vb, pa0, pa1, pa2, pa3); pv_one<3>(o[3], vb, pa0, pa1, pa2, pa3);
; template <bool BANDED, bool FIXED> ...
;     ...
;     pv_d0(o, vb0, pa0, pa1, pa2, pa3); partialSM<FIXED, !BANDED>(pB0, pB1, m_reg, mnB, alB);
;     __syncthreads(); SWAIT(); SWRITE(0, SE);
;     RESC(alB); __syncthreads();
;     SBAR(); if (FIXED) qkt_c(pA0, pA1, K_lds, qr, r32, hi); else qkt(pA0, pA1, K_lds, qr, r32, hi, 0.f); MASK(pA0, pA1, j + 1);
;     finishSM(pB0, pB1, alB, l_reg, pa0, pa1, pa2, pa3); SBAR();
	s_nop 0
	v_mfma_f32_32x32x16_bf16 v[16:31], v[80:83], v[210:213], v[16:31]
	ds_read_b64_tr_b16 v[210:211], v255 offset:0x200
	ds_read_b64_tr_b16 v[212:213], v255 offset:0xa00
	v_mfma_f32_32x32x16_bf16 v[16:31], v[84:87], v[214:217], v[16:31]
	ds_read_b64_tr_b16 v[214:215], v255 offset:0x1200
	ds_read_b64_tr_b16 v[216:217], v255 offset:0x1a00
	v_mfma_f32_32x32x16_bf16 v[16:31], v[88:91], v[218:221], v[16:31]
	ds_read_b64_tr_b16 v[218:219], v255 offset:0x2200
	ds_read_b64_tr_b16 v[220:221], v255 offset:0x2a00
	v_mfma_f32_32x32x16_bf16 v[16:31], v[92:95], v[222:225], v[16:31]
	ds_read_b64_tr_b16 v[222:223], v255 offset:0x3200
	ds_read_b64_tr_b16 v[224:225], v255 offset:0x3a00
	s_waitcnt lgkmcnt(0)
	v_mfma_f32_32x32x16_bf16 v[32:47], v[80:83], v[210:213], v[32:47]
	ds_read_b64_tr_b16 v[210:211], v255 offset:0x400
	ds_read_b64_tr_b16 v[212:213], v255 offset:0xc00
	v_mfma_f32_32x32x16_bf16 v[32:47], v[84:87], v[214:217], v[32:47]
	ds_read_b64_tr_b16 v[214:215], v255 offset:0x1400
	ds_read_b64_tr_b16 v[216:217], v255 offset:0x1c00
	v_mfma_f32_32x32x16_bf16 v[32:47], v[88:91], v[218:221], v[32:47]
	ds_read_b64_tr_b16 v[218:219], v255 offset:0x2400
	ds_read_b64_tr_b16 v[220:221], v255 offset:0x2c00
	v_mfma_f32_32x32x16_bf16 v[32:47], v[92:95], v[222:225], v[32:47]
	ds_read_b64_tr_b16 v[222:223], v255 offset:0x3400
	ds_read_b64_tr_b16 v[224:225], v255 offset:0x3c00
	s_waitcnt lgkmcnt(0)
	v_mfma_f32_32x32x16_bf16 v[48:63], v[80:83], v[210:213], v[48:63]
	ds_read_b64_tr_b16 v[210:211], v255 offset:0x600
	ds_read_b64_tr_b16 v[212:213], v255 offset:0xe00
	v_mfma_f32_32x32x16_bf16 v[48:63], v[84:87], v[214:217], v[48:63]
	ds_read_b64_tr_b16 v[214:215], v255 offset:0x1600
	ds_read_b64_tr_b16 v[216:217], v255 offset:0x1e00
	v_mfma_f32_32x32x16_bf16 v[48:63], v[88:91], v[218:221], v[48:63]
	ds_read_b64_tr_b16 v[218:219], v255 offset:0x2600
	ds_read_b64_tr_b16 v[220:221], v255 offset:0x2e00
	v_mfma_f32_32x32x16_bf16 v[48:63], v[92:95], v[222:225], v[48:63]
	ds_read_b64_tr_b16 v[222:223], v255 offset:0x3600
	ds_read_b64_tr_b16 v[224:225], v255 offset:0x3e00
	s_waitcnt lgkmcnt(0)
	v_mfma_f32_32x32x16_bf16 v[64:79], v[80:83], v[210:213], v[64:79]
	v_exp_f32_e32 v210, v112
	v_exp_f32_e32 v211, v113
	v_exp_f32_e32 v212, v114
	v_exp_f32_e32 v213, v115
	v_mfma_f32_32x32x16_bf16 v[64:79], v[84:87], v[214:217], v[64:79]
	v_exp_f32_e32 v214, v116
	v_exp_f32_e32 v215, v117
	v_exp_f32_e32 v216, v118
	v_exp_f32_e32 v217, v119
	v_mfma_f32_32x32x16_bf16 v[64:79], v[88:91], v[218:221], v[64:79]
	v_exp_f32_e32 v218, v120
	v_exp_f32_e32 v219, v121
	v_exp_f32_e32 v220, v122
	v_exp_f32_e32 v221, v123
	s_mov_b32 s100, vcc_lo
	s_mov_b32 vcc_lo, vcc_hi
	s_mov_b32 vcc_hi, s101
	s_mov_b32 s101, s100
	s_waitcnt lgkmcnt(0)
	s_barrier
	v_mfma_f32_32x32x16_bf16 v[64:79], v[92:95], v[222:225], v[64:79]
	v_exp_f32_e32 v222, v124
	v_exp_f32_e32 v223, v125
	v_exp_f32_e32 v224, v126
	v_exp_f32_e32 v225, v127
	v_exp_f32_e32 v168, v104
	v_exp_f32_e32 v169, v105
	ds_read_b128 v[80:83], v200 offset:32768
	ds_read_b128 v[84:87], v200 offset:40960
	ds_read_b128 v[160:163], v201 offset:32768
	ds_read_b128 v[164:167], v201 offset:40960
	s_waitcnt lgkmcnt(3)
	v_mfma_f32_32x32x16_bf16 v[112:127], v[80:83], v[156:159], 0
	v_exp_f32_e32 v170, v106
	v_exp_f32_e32 v171, v107
	v_exp_f32_e32 v172, v108
	v_exp_f32_e32 v173, v109
	v_exp_f32_e32 v174, v110
	v_exp_f32_e32 v111, v111
	v_cvt_pk_bf16_f32 v108, v168, v169
	s_waitcnt lgkmcnt(2)
	v_mfma_f32_32x32x16_bf16 v[80:95], v[84:87], v[156:159], 0
	ds_read_b128 v[188:191], v202 offset:32768
	ds_read_b128 v[192:195], v202 offset:40960
	v_cvt_pk_bf16_f32 v109, v170, v171
	v_cvt_pk_bf16_f32 v110, v172, v173
	s_nop 1
	v_permlane32_swap_b32_e32 v108, v110
	s_waitcnt lgkmcnt(3)
	v_mfma_f32_32x32x16_bf16 v[112:127], v[160:163], v[152:155], v[112:127]
	s_waitcnt lgkmcnt(2)
	v_mfma_f32_32x32x16_bf16 v[80:95], v[164:167], v[152:155], v[80:95]
	ds_read_b128 v[160:163], v203 offset:32768
	ds_read_b128 v[164:167], v203 offset:40960
	v_add_u32_e32 v254, vcc_lo, v184
	v_add_u32_e32 v255, vcc_lo, v185
	s_waitcnt vmcnt(0)
	ds_write_b128 v254, v[2:5]
	s_waitcnt lgkmcnt(4)
	v_mfma_f32_32x32x16_bf16 v[112:127], v[188:191], v[148:151], v[112:127]
	s_waitcnt lgkmcnt(3)
	v_mfma_f32_32x32x16_bf16 v[80:95], v[192:195], v[148:151], v[80:95]
	ds_read_b128 v[188:191], v206 offset:32768
	ds_read_b128 v[192:195], v206 offset:40960
	ds_write_b128 v255, v[6:9]
	s_waitcnt lgkmcnt(5)
	v_mfma_f32_32x32x16_bf16 v[112:127], v[160:163], v[144:147], v[112:127]
	s_waitcnt lgkmcnt(4)
	v_mfma_f32_32x32x16_bf16 v[80:95], v[164:167], v[144:147], v[80:95]
	ds_read_b128 v[160:163], v204 offset:32768
	ds_read_b128 v[164:167], v204 offset:40960
	ds_write_b128 v198, v[10:13] offset:49152
	s_waitcnt lgkmcnt(5)
	v_mfma_f32_32x32x16_bf16 v[112:127], v[188:191], v[140:143], v[112:127]
	s_waitcnt lgkmcnt(4)
	v_mfma_f32_32x32x16_bf16 v[80:95], v[192:195], v[140:143], v[80:95]
	ds_read_b128 v[188:191], v205 offset:32768
	ds_read_b128 v[192:195], v205 offset:40960
	ds_write_b128 v199, v[176:179] offset:49152
	s_waitcnt lgkmcnt(5)
	v_mfma_f32_32x32x16_bf16 v[112:127], v[160:163], v[136:139], v[112:127]
	s_waitcnt lgkmcnt(4)
	v_mfma_f32_32x32x16_bf16 v[80:95], v[164:167], v[136:139], v[80:95]
	ds_read_b128 v[160:163], v207 offset:32768
	ds_read_b128 v[164:167], v207 offset:40960
	s_waitcnt lgkmcnt(4)
	v_mfma_f32_32x32x16_bf16 v[112:127], v[188:191], v[132:135], v[112:127]
	s_waitcnt lgkmcnt(3)
	v_mfma_f32_32x32x16_bf16 v[80:95], v[192:195], v[132:135], v[80:95]
	s_waitcnt lgkmcnt(1)
; #define SBAR() __builtin_amdgcn_sched_barrier(0)
; __device__ __forceinline__ void finishSM(f32x16& p0, f32x16& p1, float alpha, float& l_reg, bf16x8& pa0, bf16x8& pa1, bf16x8& pa2, bf16x8& pa3) {
; #pragma unroll
;   for (int r = 0; r < 16; ++r) p1[r] = __builtin_amdgcn_exp2f(p1[r]);
;   float ps = 0;
; #pragma unroll
;   for (int r = 0; r < 16; ++r) ps += p0[r];
; #pragma unroll
;   for (int r = 0; r < 16; ++r) ps += p1[r];
;   { auto rr = __builtin_amdgcn_permlane32_swap(__float_as_uint(ps), __float_as_uint(ps), false, false);
;     ps = __uint_as_float(rr[0]) + __uint_as_float(rr[1]); }
;   l_reg = l_reg * alpha + ps;
;     ...
;   PK4(p0, 0, pa0); PK4(p0, 8, pa1); PK4(p1, 0, pa2); PK4(p1, 8, pa3);
; template <int D0> __device__ __forceinline__ void pv_one(f32x16& od, int vb, bf16x8 pa0, bf16x8 pa1, bf16x8 pa2, bf16x8 pa3) {
;   const s16x4 l0 = tr_read<v_rd_off(D0, 0, 0)>(vb), h0 = tr_read<v_rd_off(D0, 0, 1)>(vb), l1 = tr_read<v_rd_off(D0, 1, 0)>(vb), h1 = tr_read<v_rd_off(D0, 1, 1)>(vb);
;   const s16x4 l2 = tr_read<v_rd_off(D0, 2, 0)>(vb), h2 = tr_read<v_rd_off(D0, 2, 1)>(vb), l3 = tr_read<v_rd_off(D0, 3, 0)>(vb), h3 = tr_read<v_rd_off(D0, 3, 1)>(vb);
;   asm volatile("s_waitcnt lgkmcnt(0)" ::: "memory"); SBAR();
;     ...
;   od = __builtin_amdgcn_mfma_f32_32x32x16_bf16(pa0, PK(l0, h0), od, 0, 0, 0);
;   od = __builtin_amdgcn_mfma_f32_32x32x16_bf16(pa1, PK(l1, h1), od, 0, 0, 0);
;   od = __builtin_amdgcn_mfma_f32_32x32x16_bf16(pa2, PK(l2, h2), od, 0, 0, 0);
;   od = __builtin_amdgcn_mfma_f32_32x32x16_bf16(pa3, PK(l3, h3), od, 0, 0, 0);
;     ...
; }
; __device__ __forceinline__ void pv_d0(f32x16* o, int vb, bf16x8 pa0, bf16x8 pa1, bf16x8 pa2, bf16x8 pa3) {
;   pv_one<0>(o[0], vb, pa0, pa1, pa2, pa3); pv_one<1>(o[1], vb, pa0, pa1, pa2, pa3); pv_one<2>(o[2], vb, pa0, pa1, pa2, pa3); pv_one<3>(o[3], vb, pa0, pa1, pa2, pa3);
	v_mfma_f32_32x32x16_bf16 v[112:127], v[160:163], v[128:131], v[112:127]
	v_exp_f32_e32 v160, v96
	v_add_f32_e32 v96, 0, v210
	v_add_f32_e32 v96, v211, v96
	v_add_f32_e32 v96, v212, v96
	v_add_f32_e32 v96, v213, v96
	v_add_f32_e32 v96, v214, v96
	v_add_f32_e32 v96, v215, v96
	v_add_f32_e32 v96, v216, v96
	v_add_f32_e32 v96, v217, v96
	v_add_f32_e32 v96, v218, v96
	v_add_f32_e32 v96, v219, v96
	v_add_f32_e32 v96, v220, v96
	v_add_f32_e32 v96, v221, v96
	v_add_f32_e32 v96, v222, v96
	v_exp_f32_e32 v161, v97
	v_add_f32_e32 v96, v223, v96
	v_exp_f32_e32 v162, v98
	v_add_f32_e32 v96, v224, v96
	v_exp_f32_e32 v163, v99
	v_add_f32_e32 v96, v225, v96
	s_waitcnt lgkmcnt(0)
	v_mfma_f32_32x32x16_bf16 v[80:95], v[164:167], v[128:131], v[80:95]
	v_exp_f32_e32 v164, v100
	v_add_f32_e32 v96, v160, v96
	v_exp_f32_e32 v165, v101
	v_add_f32_e32 v96, v161, v96
	v_exp_f32_e32 v166, v102
	v_add_f32_e32 v96, v162, v96
	v_exp_f32_e32 v167, v103
	v_add_f32_e32 v96, v163, v96
	v_add_f32_e32 v96, v164, v96
	v_add_f32_e32 v96, v165, v96
	v_add_f32_e32 v96, v166, v96
	v_add_f32_e32 v96, v167, v96
	v_add_f32_e32 v96, v168, v96
	v_add_f32_e32 v96, v169, v96
	v_add_f32_e32 v96, v170, v96
	v_add_f32_e32 v96, v171, v96
	v_add_f32_e32 v96, v172, v96
	v_add_f32_e32 v96, v173, v96
	v_add_f32_e32 v96, v174, v96
	v_add_f32_e32 v96, v111, v96
	v_mov_b32_e32 v97, v96
	s_nop 1
	v_permlane32_swap_b32_e32 v96, v97
	v_add_f32_e32 v96, v96, v97
	v_add_f32_e32 v183, v226, v96
	v_cvt_pk_bf16_f32 v96, v210, v211
	v_cvt_pk_bf16_f32 v97, v212, v213
	v_cvt_pk_bf16_f32 v98, v214, v215
	v_cvt_pk_bf16_f32 v99, v216, v217
	v_cvt_pk_bf16_f32 v100, v218, v219
	v_cvt_pk_bf16_f32 v101, v220, v221
	v_cvt_pk_bf16_f32 v102, v222, v223
	v_cvt_pk_bf16_f32 v103, v224, v225
	v_cvt_pk_bf16_f32 v104, v160, v161
	v_cvt_pk_bf16_f32 v105, v162, v163
	v_cvt_pk_bf16_f32 v106, v164, v165
	v_cvt_pk_bf16_f32 v107, v166, v167
	v_cvt_pk_bf16_f32 v111, v174, v111
	s_nop 0
	v_permlane32_swap_b32_e32 v96, v98
	v_permlane32_swap_b32_e32 v97, v99
	v_permlane32_swap_b32_e32 v100, v102
	v_permlane32_swap_b32_e32 v101, v103
	v_permlane32_swap_b32_e32 v104, v106
	v_permlane32_swap_b32_e32 v105, v107
	v_permlane32_swap_b32_e32 v109, v111
	s_min_u32 s40, s2, 0xfc
	s_add_i32 s100, s40, 3
	s_mul_i32 s100, s100, 0x60000
	v_add_u32_e32 v254, s100, v14
	v_add_u32_e32 v255, s100, v15
	global_load_dwordx4 v[160:163], v254, s[58:59]
	global_load_dwordx4 v[164:167], v255, s[58:59]
	global_load_dwordx4 v[168:171], v254, s[8:9]
	global_load_dwordx4 v[172:175], v255, s[8:9]
	v_add_u32_e32 v255, vcc_hi, v208
	ds_read_b64_tr_b16 v[210:211], v255 offset:0
	ds_read_b64_tr_b16 v[212:213], v255 offset:0x800
	ds_read_b64_tr_b16 v[214:215], v255 offset:0x1000
	ds_read_b64_tr_b16 v[216:217], v255 offset:0x1800
	ds_read_b64_tr_b16 v[218:219], v255 offset:0x2000
	ds_read_b64_tr_b16 v[220:221], v255 offset:0x2800
	ds_read_b64_tr_b16 v[222:223], v255 offset:0x3000
	ds_read_b64_tr_b16 v[224:225], v255 offset:0x3800
	s_waitcnt lgkmcnt(0)
	s_nop 0
	v_mfma_f32_32x32x16_bf16 v[16:31], v[96:99], v[210:213], v[16:31]
	ds_read_b64_tr_b16 v[210:211], v255 offset:0x200
	ds_read_b64_tr_b16 v[212:213], v255 offset:0xa00
	v_mfma_f32_32x32x16_bf16 v[16:31], v[100:103], v[214:217], v[16:31]
	ds_read_b64_tr_b16 v[214:215], v255 offset:0x1200
	ds_read_b64_tr_b16 v[216:217], v255 offset:0x1a00
	v_mfma_f32_32x32x16_bf16 v[16:31], v[104:107], v[218:221], v[16:31]
	ds_read_b64_tr_b16 v[218:219], v255 offset:0x2200
	ds_read_b64_tr_b16 v[220:221], v255 offset:0x2a00
	v_mfma_f32_32x32x16_bf16 v[16:31], v[108:111], v[222:225], v[16:31]
	ds_read_b64_tr_b16 v[222:223], v255 offset:0x3200
	ds_read_b64_tr_b16 v[224:225], v255 offset:0x3a00
	s_waitcnt lgkmcnt(0)
	v_mfma_f32_32x32x16_bf16 v[32:47], v[96:99], v[210:213], v[32:47]
	ds_read_b64_tr_b16 v[210:211], v255 offset:0x400
	ds_read_b64_tr_b16 v[212:213], v255 offset:0xc00
	v_mfma_f32_32x32x16_bf16 v[32:47], v[100:103], v[214:217], v[32:47]
	ds_read_b64_tr_b16 v[214:215], v255 offset:0x1400
	ds_read_b64_tr_b16 v[216:217], v255 offset:0x1c00
	v_mfma_f32_32x32x16_bf16 v[32:47], v[104:107], v[218:221], v[32:47]
	ds_read_b64_tr_b16 v[218:219], v255 offset:0x2400
	ds_read_b64_tr_b16 v[220:221], v255 offset:0x2c00
	v_mfma_f32_32x32x16_bf16 v[32:47], v[108:111], v[222:225], v[32:47]
	ds_read_b64_tr_b16 v[222:223], v255 offset:0x3400
	ds_read_b64_tr_b16 v[224:225], v255 offset:0x3c00
	s_waitcnt lgkmcnt(0)
	v_mfma_f32_32x32x16_bf16 v[48:63], v[96:99], v[210:213], v[48:63]
	ds_read_b64_tr_b16 v[210:211], v255 offset:0x600
	ds_read_b64_tr_b16 v[212:213], v255 offset:0xe00
	v_mfma_f32_32x32x16_bf16 v[48:63], v[100:103], v[214:217], v[48:63]
	ds_read_b64_tr_b16 v[214:215], v255 offset:0x1600
	ds_read_b64_tr_b16 v[216:217], v255 offset:0x1e00
	v_mfma_f32_32x32x16_bf16 v[48:63], v[104:107], v[218:221], v[48:63]
	ds_read_b64_tr_b16 v[218:219], v255 offset:0x2600
	ds_read_b64_tr_b16 v[220:221], v255 offset:0x2e00
	v_mfma_f32_32x32x16_bf16 v[48:63], v[108:111], v[222:225], v[48:63]
	ds_read_b64_tr_b16 v[222:223], v255 offset:0x3600
	ds_read_b64_tr_b16 v[224:225], v255 offset:0x3e00
	s_waitcnt lgkmcnt(0)
	v_mfma_f32_32x32x16_bf16 v[64:79], v[96:99], v[210:213], v[64:79]
	v_exp_f32_e32 v210, v124
	v_exp_f32_e32 v213, v125
	v_exp_f32_e32 v211, v126
	v_exp_f32_e32 v212, v127
	v_mfma_f32_32x32x16_bf16 v[64:79], v[100:103], v[214:217], v[64:79]
	v_exp_f32_e32 v215, v120
	v_exp_f32_e32 v217, v121
	v_exp_f32_e32 v214, v122
	v_exp_f32_e32 v216, v123
	s_cmpk_gt_u32 s2, 0xfc
	v_mfma_f32_32x32x16_bf16 v[64:79], v[104:107], v[218:221], v[64:79]
	v_exp_f32_e32 v221, v114
	v_exp_f32_e32 v220, v116
	v_exp_f32_e32 v218, v118
	v_exp_f32_e32 v219, v119
	s_mov_b32 s100, vcc_lo
	s_mov_b32 vcc_lo, vcc_hi
	s_mov_b32 vcc_hi, s101
	s_mov_b32 s101, s100
	s_waitcnt lgkmcnt(0)
	s_barrier
; #define SBAR() __builtin_amdgcn_sched_barrier(0)
; #define RESC(a) do { if (!FIXED && __any((a) < 1.f)) { if (hi == 0) al_l[r32] = (a); asm volatile("s_waitcnt lgkmcnt(0)" ::: "memory"); \
;     _Pragma("unroll") for (int d = 0; d < 4; ++d) _Pragma("unroll") for (int r = 0; r < 16; ++r) o[d][r] *= al_l[crow(r, hi)]; } } while (0)
; #define MASK(P0, P1, t) do { if (BANDED) band_mask(P0, P1, rel00 + (t) * KVBLK, mlo, mhi); } while (0)
; __device__ __forceinline__ void qkt_c(f32x16& p0, f32x16& p1, const bf16* Ks, const bf16x8* qr, int r32, int hi) {
;   const f32x16 cinit = {};
; #pragma unroll
;   for (int d0 = 0; d0 < 8; ++d0) { int cb = (d0 * 16 + hi * 8) * 2;
;     bf16x8 b0 = *reinterpret_cast<const bf16x8*>((const char*)Ks + KSWZ(r32, cb));
;     bf16x8 b1 = *reinterpret_cast<const bf16x8*>((const char*)Ks + KSWZ(32 + r32, cb));
;     p0 = __builtin_amdgcn_mfma_f32_32x32x16_bf16(b0, qr[d0], d0 == 0 ? cinit : p0, 0, 0, 0);
;     p1 = __builtin_amdgcn_mfma_f32_32x32x16_bf16(b1, qr[d0], d0 == 0 ? cinit : p1, 0, 0, 0); }
; }
; template <bool BANDED, bool FIXED> ...
;     ...
;   }
;   SBAR(); if (FIXED) qkt_c(pB0, pB1, (bf16*)((char*)K_lds + SHM_K), qr, r32, hi); else qkt(pB0, pB1, (bf16*)((char*)K_lds + SHM_K), qr, r32, hi, 0.f); MASK(pB0, pB1, NT - 1);
;   finishSM(pA0, pA1, alA, l_reg, pa0, pa1, pa2, pa3); SBAR();
;   pv_d0(o, vb0, pa0, pa1, pa2, pa3); partialSM<FIXED, !BANDED>(pB0, pB1, m_reg, mnB, alB);
;   __syncthreads(); RESC(alB);
;   finishSM(pB0, pB1, alB, l_reg, pa0, pa1, pa2, pa3); SBAR();
	ds_read_b128 v[2:5], v200 offset:49152
	ds_read_b128 v[6:9], v200 offset:57344
	v_mfma_f32_32x32x16_bf16 v[64:79], v[108:111], v[222:225], v[64:79]
	v_exp_f32_e32 v223, v112
	v_exp_f32_e32 v225, v113
	v_exp_f32_e32 v224, v115
	v_exp_f32_e32 v222, v117
	s_cbranch_scc0 .LBB0_118
	v_mov_b32_e32 v188, 0x3c0881c4
	v_mov_b32_e32 v189, 0xbab64f3b
	v_mov_b32_e32 v190, 1
	v_bfrev_b32_e32 v191, 0.5
	v_mov_b32_e32 v192, 0xf149f2ca
	v_mov_b32_e32 v193, 0xff800000
	v_mov_b32_e32 v194, 0x41b17218
	v_not_b32_e32 v195, 63
	v_add_u32_e32 v255, vcc_hi, v208
	v_add_u32_e32 v254, s101, v208
	v_exp_f32_e32 v12, v80
	v_exp_f32_e32 v13, v81
	v_exp_f32_e32 v14, v82
	s_waitcnt lgkmcnt(1)
	v_mfma_f32_32x32x16_bf16 v[112:127], v[2:5], v[156:159], 0
	v_exp_f32_e32 v15, v83
	v_exp_f32_e32 v80, v84
	v_exp_f32_e32 v81, v85
	v_exp_f32_e32 v82, v86
	v_exp_f32_e32 v83, v87
	v_exp_f32_e32 v84, v88
	v_exp_f32_e32 v85, v89
	s_waitcnt lgkmcnt(0)
	v_mfma_f32_32x32x16_bf16 v[96:111], v[6:9], v[156:159], 0
	ds_read_b128 v[2:5], v201 offset:49152
	ds_read_b128 v[6:9], v201 offset:57344
	v_exp_f32_e32 v86, v90
	v_exp_f32_e32 v87, v91
	v_exp_f32_e32 v88, v92
	v_exp_f32_e32 v89, v93
	v_exp_f32_e32 v90, v94
	v_exp_f32_e32 v91, v95
	s_waitcnt lgkmcnt(1)
	v_mfma_f32_32x32x16_bf16 v[112:127], v[2:5], v[152:155], v[112:127]
	v_cvt_pk_bf16_f32 v10, v210, v213
	v_cvt_pk_bf16_f32 v11, v211, v212
	s_waitcnt lgkmcnt(0)
	v_mfma_f32_32x32x16_bf16 v[96:111], v[6:9], v[152:155], v[96:111]
	ds_read_b128 v[2:5], v202 offset:49152
	ds_read_b128 v[6:9], v202 offset:57344
	s_waitcnt lgkmcnt(1)
	v_mfma_f32_32x32x16_bf16 v[112:127], v[2:5], v[148:151], v[112:127]
	s_waitcnt lgkmcnt(0)
	v_mfma_f32_32x32x16_bf16 v[96:111], v[6:9], v[148:151], v[96:111]
	ds_read_b128 v[2:5], v203 offset:49152
	ds_read_b128 v[6:9], v203 offset:57344
	s_waitcnt lgkmcnt(1)
	v_mfma_f32_32x32x16_bf16 v[112:127], v[2:5], v[144:147], v[112:127]
	s_waitcnt lgkmcnt(0)
	v_mfma_f32_32x32x16_bf16 v[96:111], v[6:9], v[144:147], v[96:111]
	ds_read_b128 v[2:5], v206 offset:49152
	ds_read_b128 v[6:9], v206 offset:57344
	s_waitcnt lgkmcnt(1)
	v_mfma_f32_32x32x16_bf16 v[112:127], v[2:5], v[140:143], v[112:127]
	s_waitcnt lgkmcnt(0)
	v_mfma_f32_32x32x16_bf16 v[96:111], v[6:9], v[140:143], v[96:111]
	ds_read_b128 v[2:5], v204 offset:49152
	ds_read_b128 v[6:9], v204 offset:57344
	s_waitcnt lgkmcnt(1)
	v_mfma_f32_32x32x16_bf16 v[112:127], v[2:5], v[136:139], v[112:127]
	s_waitcnt lgkmcnt(0)
	v_mfma_f32_32x32x16_bf16 v[96:111], v[6:9], v[136:139], v[96:111]
	ds_read_b128 v[2:5], v205 offset:49152
	ds_read_b128 v[6:9], v205 offset:57344
	s_waitcnt lgkmcnt(1)
	v_mfma_f32_32x32x16_bf16 v[112:127], v[2:5], v[132:135], v[112:127]
	s_waitcnt lgkmcnt(0)
	v_mfma_f32_32x32x16_bf16 v[96:111], v[6:9], v[132:135], v[96:111]
	ds_read_b128 v[2:5], v207 offset:49152
	ds_read_b128 v[6:9], v207 offset:57344
	s_waitcnt lgkmcnt(1)
	v_mfma_f32_32x32x16_bf16 v[112:127], v[2:5], v[128:131], v[112:127]
	v_add_f32_e32 v2, 0, v223
	v_add_f32_e32 v2, v225, v2
	v_add_f32_e32 v2, v221, v2
	v_add_f32_e32 v2, v224, v2
	v_add_f32_e32 v2, v220, v2
	v_add_f32_e32 v2, v222, v2
	v_add_f32_e32 v2, v218, v2
	v_add_f32_e32 v2, v219, v2
	v_add_f32_e32 v2, v215, v2
	v_add_f32_e32 v2, v217, v2
	v_add_f32_e32 v2, v214, v2
	v_add_f32_e32 v2, v216, v2
	v_add_f32_e32 v2, v210, v2
	v_add_f32_e32 v2, v213, v2
	v_add_f32_e32 v2, v211, v2
	v_add_f32_e32 v2, v212, v2
	v_add_f32_e32 v2, v12, v2
	v_add_f32_e32 v2, v13, v2
	v_add_f32_e32 v2, v14, v2
	v_add_f32_e32 v2, v15, v2
	v_add_f32_e32 v2, v80, v2
	v_add_f32_e32 v2, v81, v2
	v_add_f32_e32 v2, v82, v2
	v_add_f32_e32 v2, v83, v2
	v_add_f32_e32 v2, v84, v2
	v_add_f32_e32 v2, v85, v2
	v_add_f32_e32 v2, v86, v2
	v_add_f32_e32 v2, v87, v2
	v_add_f32_e32 v2, v88, v2
	v_add_f32_e32 v2, v89, v2
	v_add_f32_e32 v2, v90, v2
	v_add_f32_e32 v2, v91, v2
	s_waitcnt lgkmcnt(0)
	v_mfma_f32_32x32x16_bf16 v[96:111], v[6:9], v[128:131], v[96:111]
	v_mov_b32_e32 v3, v2
	v_cvt_pk_bf16_f32 v4, v223, v225
	v_cvt_pk_bf16_f32 v5, v221, v224
	v_cvt_pk_bf16_f32 v6, v220, v222
	v_cvt_pk_bf16_f32 v7, v218, v219
	s_nop 1
	v_permlane32_swap_b32_e32 v2, v3
	v_permlane32_swap_b32_e32 v4, v6
	v_permlane32_swap_b32_e32 v5, v7
	v_cvt_pk_bf16_f32 v8, v215, v217
	v_cvt_pk_bf16_f32 v9, v214, v216
	v_cvt_pk_bf16_f32 v12, v12, v13
	v_cvt_pk_bf16_f32 v13, v14, v15
	v_cvt_pk_bf16_f32 v14, v80, v81
	v_cvt_pk_bf16_f32 v15, v82, v83
	v_cvt_pk_bf16_f32 v80, v84, v85
	v_cvt_pk_bf16_f32 v81, v86, v87
	v_cvt_pk_bf16_f32 v82, v88, v89
	v_cvt_pk_bf16_f32 v83, v90, v91
	s_nop 0
	v_permlane32_swap_b32_e32 v8, v10
	v_permlane32_swap_b32_e32 v9, v11
	v_permlane32_swap_b32_e32 v12, v14
	v_permlane32_swap_b32_e32 v13, v15
	v_permlane32_swap_b32_e32 v80, v82
	v_permlane32_swap_b32_e32 v81, v83
	ds_read_b64_tr_b16 v[84:85], v255 offset:0
	ds_read_b64_tr_b16 v[86:87], v255 offset:0x800
	ds_read_b64_tr_b16 v[88:89], v255 offset:0x1000
	ds_read_b64_tr_b16 v[90:91], v255 offset:0x1800
	ds_read_b64_tr_b16 v[92:93], v255 offset:0x2000
	ds_read_b64_tr_b16 v[94:95], v255 offset:0x2800
	ds_read_b64_tr_b16 v[128:129], v255 offset:0x3000
	ds_read_b64_tr_b16 v[130:131], v255 offset:0x3800
	s_waitcnt lgkmcnt(0)
	s_nop 0
	v_mfma_f32_32x32x16_bf16 v[16:31], v[4:7], v[84:87], v[16:31]
	ds_read_b64_tr_b16 v[84:85], v255 offset:0x200
	ds_read_b64_tr_b16 v[86:87], v255 offset:0xa00
	v_mfma_f32_32x32x16_bf16 v[16:31], v[8:11], v[88:91], v[16:31]
	ds_read_b64_tr_b16 v[88:89], v255 offset:0x1200
	ds_read_b64_tr_b16 v[90:91], v255 offset:0x1a00
	v_mfma_f32_32x32x16_bf16 v[16:31], v[12:15], v[92:95], v[16:31]
	ds_read_b64_tr_b16 v[92:93], v255 offset:0x2200
	ds_read_b64_tr_b16 v[94:95], v255 offset:0x2a00
	v_mfma_f32_32x32x16_bf16 v[16:31], v[80:83], v[128:131], v[16:31]
	ds_read_b64_tr_b16 v[128:129], v255 offset:0x3200
	ds_read_b64_tr_b16 v[130:131], v255 offset:0x3a00
	s_waitcnt lgkmcnt(0)
; #define SBAR() __builtin_amdgcn_sched_barrier(0)
; __device__ __forceinline__ void finishSM(f32x16& p0, f32x16& p1, float alpha, float& l_reg, bf16x8& pa0, bf16x8& pa1, bf16x8& pa2, bf16x8& pa3) {
; #pragma unroll
;   for (int r = 0; r < 16; ++r) p1[r] = __builtin_amdgcn_exp2f(p1[r]);
;   float ps = 0;
; #pragma unroll
;   for (int r = 0; r < 16; ++r) ps += p0[r];
; #pragma unroll
;   for (int r = 0; r < 16; ++r) ps += p1[r];
;   { auto rr = __builtin_amdgcn_permlane32_swap(__float_as_uint(ps), __float_as_uint(ps), false, false);
;     ps = __uint_as_float(rr[0]) + __uint_as_float(rr[1]); }
;   l_reg = l_reg * alpha + ps;
;     ...
;   PK4(p0, 0, pa0); PK4(p0, 8, pa1); PK4(p1, 0, pa2); PK4(p1, 8, pa3);
; template <int D0> __device__ __forceinline__ void pv_one(f32x16& od, int vb, bf16x8 pa0, bf16x8 pa1, bf16x8 pa2, bf16x8 pa3) {
;   const s16x4 l0 = tr_read<v_rd_off(D0, 0, 0)>(vb), h0 = tr_read<v_rd_off(D0, 0, 1)>(vb), l1 = tr_read<v_rd_off(D0, 1, 0)>(vb), h1 = tr_read<v_rd_off(D0, 1, 1)>(vb);
;   const s16x4 l2 = tr_read<v_rd_off(D0, 2, 0)>(vb), h2 = tr_read<v_rd_off(D0, 2, 1)>(vb), l3 = tr_read<v_rd_off(D0, 3, 0)>(vb), h3 = tr_read<v_rd_off(D0, 3, 1)>(vb);
;   asm volatile("s_waitcnt lgkmcnt(0)" ::: "memory"); SBAR();
;     ...
;   od = __builtin_amdgcn_mfma_f32_32x32x16_bf16(pa0, PK(l0, h0), od, 0, 0, 0);
;   od = __builtin_amdgcn_mfma_f32_32x32x16_bf16(pa1, PK(l1, h1), od, 0, 0, 0);
;   od = __builtin_amdgcn_mfma_f32_32x32x16_bf16(pa2, PK(l2, h2), od, 0, 0, 0);
;   od = __builtin_amdgcn_mfma_f32_32x32x16_bf16(pa3, PK(l3, h3), od, 0, 0, 0);
;     ...
; }
; __device__ __forceinline__ void pv_d0(f32x16* o, int vb, bf16x8 pa0, bf16x8 pa1, bf16x8 pa2, bf16x8 pa3) {
;   pv_one<0>(o[0], vb, pa0, pa1, pa2, pa3); pv_one<1>(o[1], vb, pa0, pa1, pa2, pa3); pv_one<2>(o[2], vb, pa0, pa1, pa2, pa3); pv_one<3>(o[3], vb, pa0, pa1, pa2, pa3);
	v_mfma_f32_32x32x16_bf16 v[32:47], v[4:7], v[84:87], v[32:47]
	ds_read_b64_tr_b16 v[84:85], v255 offset:0x400
	ds_read_b64_tr_b16 v[86:87], v255 offset:0xc00
	v_mfma_f32_32x32x16_bf16 v[32:47], v[8:11], v[88:91], v[32:47]
	ds_read_b64_tr_b16 v[88:89], v255 offset:0x1400
	ds_read_b64_tr_b16 v[90:91], v255 offset:0x1c00
	v_mfma_f32_32x32x16_bf16 v[32:47], v[12:15], v[92:95], v[32:47]
	ds_read_b64_tr_b16 v[92:93], v255 offset:0x2400
	ds_read_b64_tr_b16 v[94:95], v255 offset:0x2c00
	v_mfma_f32_32x32x16_bf16 v[32:47], v[80:83], v[128:131], v[32:47]
	ds_read_b64_tr_b16 v[128:129], v255 offset:0x3400
	ds_read_b64_tr_b16 v[130:131], v255 offset:0x3c00
	s_waitcnt lgkmcnt(0)
	v_mfma_f32_32x32x16_bf16 v[48:63], v[4:7], v[84:87], v[48:63]
	ds_read_b64_tr_b16 v[84:85], v255 offset:0x600
	ds_read_b64_tr_b16 v[86:87], v255 offset:0xe00
	v_mfma_f32_32x32x16_bf16 v[48:63], v[8:11], v[88:91], v[48:63]
	ds_read_b64_tr_b16 v[88:89], v255 offset:0x1600
	ds_read_b64_tr_b16 v[90:91], v255 offset:0x1e00
	v_mfma_f32_32x32x16_bf16 v[48:63], v[12:15], v[92:95], v[48:63]
	ds_read_b64_tr_b16 v[92:93], v255 offset:0x2600
	ds_read_b64_tr_b16 v[94:95], v255 offset:0x2e00
	v_mfma_f32_32x32x16_bf16 v[48:63], v[80:83], v[128:131], v[48:63]
	ds_read_b64_tr_b16 v[128:129], v255 offset:0x3600
	ds_read_b64_tr_b16 v[130:131], v255 offset:0x3e00
	s_waitcnt lgkmcnt(0)
	v_mfma_f32_32x32x16_bf16 v[64:79], v[4:7], v[84:87], v[64:79]
	v_exp_f32_e32 v6, v112
	v_exp_f32_e32 v7, v113
	v_exp_f32_e32 v84, v126
	v_exp_f32_e32 v85, v127
	v_add_f32_e32 v4, 0, v6
	v_add_f32_e32 v4, v7, v4
	v_exp_f32_e32 v86, v96
	v_mfma_f32_32x32x16_bf16 v[64:79], v[8:11], v[88:91], v[64:79]
	v_exp_f32_e32 v8, v114
	v_exp_f32_e32 v9, v115
	v_exp_f32_e32 v10, v116
	v_exp_f32_e32 v11, v117
	v_add_f32_e32 v4, v8, v4
	v_add_f32_e32 v4, v9, v4
	v_add_f32_e32 v4, v10, v4
	v_mfma_f32_32x32x16_bf16 v[64:79], v[12:15], v[92:95], v[64:79]
	v_exp_f32_e32 v12, v118
	v_exp_f32_e32 v13, v119
	v_exp_f32_e32 v14, v120
	v_exp_f32_e32 v15, v121
	v_add_f32_e32 v4, v11, v4
	v_add_f32_e32 v4, v12, v4
	v_add_f32_e32 v4, v13, v4
	v_mfma_f32_32x32x16_bf16 v[64:79], v[80:83], v[128:131], v[64:79]
	v_exp_f32_e32 v80, v122
	v_exp_f32_e32 v81, v123
	v_exp_f32_e32 v82, v124
	v_add_f32_e32 v4, v14, v4
	v_exp_f32_e32 v83, v125
	v_add_f32_e32 v4, v15, v4
	v_add_f32_e32 v4, v80, v4
	v_add_f32_e32 v4, v81, v4
	v_add_f32_e32 v4, v82, v4
	v_exp_f32_e32 v87, v97
	v_add_f32_e32 v4, v83, v4
	v_exp_f32_e32 v88, v98
	v_add_f32_e32 v4, v84, v4
	v_exp_f32_e32 v89, v99
	v_add_f32_e32 v4, v85, v4
	v_exp_f32_e32 v90, v100
	v_add_f32_e32 v4, v86, v4
	v_exp_f32_e32 v91, v101
	v_add_f32_e32 v4, v87, v4
	v_exp_f32_e32 v92, v102
	v_add_f32_e32 v4, v88, v4
	v_exp_f32_e32 v93, v103
	v_add_f32_e32 v4, v89, v4
	v_exp_f32_e32 v94, v104
	v_add_f32_e32 v4, v90, v4
	v_exp_f32_e32 v95, v105
	v_add_f32_e32 v4, v91, v4
	v_exp_f32_e32 v96, v106
	v_add_f32_e32 v4, v92, v4
	v_exp_f32_e32 v97, v107
	v_add_f32_e32 v4, v93, v4
	v_exp_f32_e32 v98, v108
	v_add_f32_e32 v4, v94, v4
	v_exp_f32_e32 v99, v109
	v_add_f32_e32 v4, v95, v4
	v_exp_f32_e32 v100, v110
	v_add_f32_e32 v4, v96, v4
	v_exp_f32_e32 v101, v111
	v_add_f32_e32 v4, v97, v4
	v_add_f32_e32 v4, v98, v4
	v_add_f32_e32 v4, v99, v4
	v_add_f32_e32 v4, v100, v4
	v_add_f32_e32 v4, v101, v4
	v_mov_b32_e32 v5, v4
	s_nop 1
	v_permlane32_swap_b32_e32 v4, v5
	v_cvt_pk_bf16_f32 v6, v6, v7
	v_cvt_pk_bf16_f32 v7, v8, v9
	v_cvt_pk_bf16_f32 v8, v10, v11
	v_cvt_pk_bf16_f32 v9, v12, v13
	v_cvt_pk_bf16_f32 v10, v14, v15
	v_cvt_pk_bf16_f32 v11, v80, v81
	v_cvt_pk_bf16_f32 v12, v82, v83
	v_cvt_pk_bf16_f32 v13, v84, v85
	v_cvt_pk_bf16_f32 v80, v86, v87
	v_cvt_pk_bf16_f32 v81, v88, v89
	v_cvt_pk_bf16_f32 v82, v90, v91
	v_cvt_pk_bf16_f32 v83, v92, v93
	v_cvt_pk_bf16_f32 v84, v94, v95
	v_cvt_pk_bf16_f32 v85, v96, v97
	v_cvt_pk_bf16_f32 v86, v98, v99
	v_cvt_pk_bf16_f32 v87, v100, v101
	s_barrier
	v_permlane32_swap_b32_e32 v6, v8
	v_permlane32_swap_b32_e32 v7, v9
	v_permlane32_swap_b32_e32 v10, v12
	v_permlane32_swap_b32_e32 v11, v13
	v_permlane32_swap_b32_e32 v80, v82
	v_permlane32_swap_b32_e32 v81, v83
	v_permlane32_swap_b32_e32 v84, v86
	v_permlane32_swap_b32_e32 v85, v87
	ds_read_b64_tr_b16 v[88:89], v254 offset:0
	ds_read_b64_tr_b16 v[90:91], v254 offset:0x800
	ds_read_b64_tr_b16 v[92:93], v254 offset:0x1000
	ds_read_b64_tr_b16 v[94:95], v254 offset:0x1800
	ds_read_b64_tr_b16 v[96:97], v254 offset:0x2000
	ds_read_b64_tr_b16 v[98:99], v254 offset:0x2800
	ds_read_b64_tr_b16 v[100:101], v254 offset:0x3000
	ds_read_b64_tr_b16 v[102:103], v254 offset:0x3800
	s_waitcnt lgkmcnt(0)
	s_nop 0
	v_mfma_f32_32x32x16_bf16 v[16:31], v[6:9], v[88:91], v[16:31]
	ds_read_b64_tr_b16 v[88:89], v254 offset:0x200
	ds_read_b64_tr_b16 v[90:91], v254 offset:0xa00
	v_mfma_f32_32x32x16_bf16 v[16:31], v[10:13], v[92:95], v[16:31]
	ds_read_b64_tr_b16 v[92:93], v254 offset:0x1200
	ds_read_b64_tr_b16 v[94:95], v254 offset:0x1a00
	v_mfma_f32_32x32x16_bf16 v[16:31], v[80:83], v[96:99], v[16:31]
	ds_read_b64_tr_b16 v[96:97], v254 offset:0x2200
	ds_read_b64_tr_b16 v[98:99], v254 offset:0x2a00
	v_mfma_f32_32x32x16_bf16 v[16:31], v[84:87], v[100:103], v[16:31]
	ds_read_b64_tr_b16 v[100:101], v254 offset:0x3200
	ds_read_b64_tr_b16 v[102:103], v254 offset:0x3a00
	s_waitcnt lgkmcnt(0)
	v_mfma_f32_32x32x16_bf16 v[32:47], v[6:9], v[88:91], v[32:47]
	ds_read_b64_tr_b16 v[88:89], v254 offset:0x400
	ds_read_b64_tr_b16 v[90:91], v254 offset:0xc00
	v_mfma_f32_32x32x16_bf16 v[32:47], v[10:13], v[92:95], v[32:47]
	ds_read_b64_tr_b16 v[92:93], v254 offset:0x1400
	ds_read_b64_tr_b16 v[94:95], v254 offset:0x1c00
	v_mfma_f32_32x32x16_bf16 v[32:47], v[80:83], v[96:99], v[32:47]
	ds_read_b64_tr_b16 v[96:97], v254 offset:0x2400
	ds_read_b64_tr_b16 v[98:99], v254 offset:0x2c00
	v_mfma_f32_32x32x16_bf16 v[32:47], v[84:87], v[100:103], v[32:47]
	ds_read_b64_tr_b16 v[100:101], v254 offset:0x3400
	ds_read_b64_tr_b16 v[102:103], v254 offset:0x3c00
	s_waitcnt lgkmcnt(0)
	v_mfma_f32_32x32x16_bf16 v[48:63], v[6:9], v[88:91], v[48:63]
	ds_read_b64_tr_b16 v[88:89], v254 offset:0x600
	ds_read_b64_tr_b16 v[90:91], v254 offset:0xe00
	v_mfma_f32_32x32x16_bf16 v[48:63], v[10:13], v[92:95], v[48:63]
	ds_read_b64_tr_b16 v[92:93], v254 offset:0x1600
	ds_read_b64_tr_b16 v[94:95], v254 offset:0x1e00
	v_mfma_f32_32x32x16_bf16 v[48:63], v[80:83], v[96:99], v[48:63]
	ds_read_b64_tr_b16 v[96:97], v254 offset:0x2600
	ds_read_b64_tr_b16 v[98:99], v254 offset:0x2e00
	v_mfma_f32_32x32x16_bf16 v[48:63], v[84:87], v[100:103], v[48:63]
	ds_read_b64_tr_b16 v[100:101], v254 offset:0x3600
	ds_read_b64_tr_b16 v[102:103], v254 offset:0x3e00
	s_waitcnt lgkmcnt(0)
	v_mfma_f32_32x32x16_bf16 v[64:79], v[6:9], v[88:91], v[64:79]
	s_and_b64 vcc, exec, s[22:23]
	v_mfma_f32_32x32x16_bf16 v[64:79], v[10:13], v[92:95], v[64:79]
	v_mfma_f32_32x32x16_bf16 v[64:79], v[80:83], v[96:99], v[64:79]
	v_mfma_f32_32x32x16_bf16 v[64:79], v[84:87], v[100:103], v[64:79]
	s_cbranch_vccz .LBB0_121
	s_setprio 0
